# NSA selected-branch loop: unmasked tiles take a hand-scheduled path where exp of the second key half and its sums/cvt are interleaved under the PV MFMAs of the first half (ks-major PV order)
# speedup vs baseline: 1.0084x; 1.0084x over previous
.LBB0_746:
	s_cmp_lt_i32 s92, 32
	s_cselect_b64 vcc, -1, 0
	s_cmp_lt_u32 s92, 64
	s_cselect_b64 s[72:73], -1, 0
	s_cmpk_lt_u32 s92, 0x60
	s_cselect_b64 s[76:77], -1, 0
	v_cndmask_b32_e64 v101, v147, v146, s[76:77]
	v_cndmask_b32_e64 v101, v101, v145, s[72:73]
	v_cndmask_b32_e32 v101, v101, v144, vcc
	s_and_b32 s76, s92, 31
	v_lshrrev_b32_e32 v225, s92, v101
	v_and_b32_e32 v225, 1, v225
	v_bfe_u32 v101, v101, s76, 1
	v_cmp_eq_u32_e64 s[72:73], 1, v225
	v_cmp_ne_u32_e32 vcc, 0, v101
	s_cbranch_vccz .LBB0_743
	s_lshl_b32 s76, s91, 14
	s_add_i32 s91, s76, 0
	v_add_u32_e32 v0, s91, v184
	ds_read_b128 v[2:5], v0
	ds_read_b128 v[6:9], v0 offset:8192
	v_add_u32_e32 v0, s91, v185
	ds_read_b128 v[10:13], v0
	ds_read_b128 v[208:211], v0 offset:8192
	v_add_u32_e32 v0, s91, v186
	ds_read_b128 v[212:215], v0
	ds_read_b128 v[216:219], v0 offset:8192
	s_waitcnt lgkmcnt(0)
	v_mfma_f32_32x32x16_bf16 v[80:95], v[2:5], v[140:143], 0
	v_mfma_f32_32x32x16_bf16 v[96:111], v[6:9], v[140:143], 0
	v_add_u32_e32 v0, s91, v183
	ds_read_b128 v[2:5], v0
	ds_read_b128 v[6:9], v0 offset:8192
	v_mfma_f32_32x32x16_bf16 v[80:95], v[10:13], v[136:139], v[80:95]
	v_mfma_f32_32x32x16_bf16 v[96:111], v[208:211], v[136:139], v[96:111]
	v_add_u32_e32 v0, s91, v182
	ds_read_b128 v[10:13], v0
	ds_read_b128 v[208:211], v0 offset:8192
	v_mfma_f32_32x32x16_bf16 v[80:95], v[212:215], v[132:135], v[80:95]
	v_mfma_f32_32x32x16_bf16 v[96:111], v[216:219], v[132:135], v[96:111]
	v_add_u32_e32 v0, s91, v181
	ds_read_b128 v[212:215], v0
	ds_read_b128 v[216:219], v0 offset:8192
	s_waitcnt lgkmcnt(0)
	v_mfma_f32_32x32x16_bf16 v[80:95], v[2:5], v[128:131], v[80:95]
	v_mfma_f32_32x32x16_bf16 v[96:111], v[6:9], v[128:131], v[96:111]
	v_add_u32_e32 v0, s91, v180
	ds_read_b128 v[2:5], v0
	ds_read_b128 v[6:9], v0 offset:8192
	v_mfma_f32_32x32x16_bf16 v[80:95], v[10:13], v[124:127], v[80:95]
	v_mfma_f32_32x32x16_bf16 v[96:111], v[208:211], v[124:127], v[96:111]
	v_add_u32_e32 v0, s91, v179
	ds_read_b128 v[10:13], v0
	ds_read_b128 v[208:211], v0 offset:8192
	v_mfma_f32_32x32x16_bf16 v[80:95], v[212:215], v[120:123], v[80:95]
	v_mfma_f32_32x32x16_bf16 v[96:111], v[216:219], v[120:123], v[96:111]
	s_waitcnt lgkmcnt(0)
	v_mfma_f32_32x32x16_bf16 v[80:95], v[2:5], v[116:119], v[80:95]
	v_mfma_f32_32x32x16_bf16 v[96:111], v[6:9], v[116:119], v[96:111]
	v_mfma_f32_32x32x16_bf16 v[80:95], v[10:13], v[112:115], v[80:95]
	v_mfma_f32_32x32x16_bf16 v[96:111], v[208:211], v[112:115], v[96:111]
	s_nop 10
	s_cmp_eq_u32 s92, s33
	s_cbranch_scc0 .Lsel_fast
	v_exp_f32_e32 v6, v80
	v_exp_f32_e32 v0, v96
	v_exp_f32_e32 v9, v81
	v_exp_f32_e32 v3, v97
	v_exp_f32_e32 v8, v82
	v_exp_f32_e32 v2, v98
	v_exp_f32_e32 v11, v83
	v_exp_f32_e32 v5, v99
	v_exp_f32_e32 v10, v84
	v_exp_f32_e32 v4, v100
	v_exp_f32_e32 v13, v85
	v_exp_f32_e32 v7, v101
	v_exp_f32_e32 v96, v86
	v_exp_f32_e32 v82, v102
	v_exp_f32_e32 v97, v87
	v_exp_f32_e32 v83, v103
	v_exp_f32_e32 v88, v88
	v_exp_f32_e32 v14, v104
	v_exp_f32_e32 v89, v89
	v_exp_f32_e32 v15, v105
	v_exp_f32_e32 v90, v90
	v_exp_f32_e32 v80, v106
	v_exp_f32_e32 v91, v91
	v_exp_f32_e32 v81, v107
	v_exp_f32_e32 v92, v92
	v_exp_f32_e32 v84, v108
	v_exp_f32_e32 v93, v93
	v_exp_f32_e32 v85, v109
	v_exp_f32_e32 v94, v94
	v_exp_f32_e32 v86, v110
	v_exp_f32_e32 v95, v95
	v_exp_f32_e32 v87, v111
	s_cmp_eq_u32 s92, s33
	s_mov_b64 s[76:77], -1
	s_cbranch_scc1 .LBB0_749
	s_mov_b64 s[76:77], 0

.Lsel_fast:
	v_add_u32_e32 v207, s91, v153
	v_add3_u32 v0, v207, v199, v178
	v_add_u32_e32 v6, s91, v200
	v_add3_u32 v6, v6, v178, v153
	v_add3_u32 v7, v207, v201, v178
	v_add_u32_e32 v230, s91, v202
	v_add3_u32 v230, v230, v178, v153
	ds_read_b64_tr_b16 v[12:13], v0 offset:32768
	ds_read_b64_tr_b16 v[14:15], v6 offset:34816
	ds_read_b64_tr_b16 v[208:209], v0 offset:36864
	ds_read_b64_tr_b16 v[210:211], v6 offset:38912
	ds_read_b64_tr_b16 v[212:213], v7 offset:32768
	ds_read_b64_tr_b16 v[214:215], v230 offset:34816
	ds_read_b64_tr_b16 v[216:217], v7 offset:36864
	ds_read_b64_tr_b16 v[218:219], v230 offset:38912
	v_add3_u32 v231, v207, v203, v178
	v_add_u32_e32 v241, s91, v204
	v_add3_u32 v241, v241, v178, v153
	v_add3_u32 v242, v207, v205, v178
	v_add_u32_e32 v243, s91, v206
	v_add3_u32 v243, v243, v178, v153
	v_exp_f32_e32 v80, v80
	v_exp_f32_e32 v81, v81
	v_exp_f32_e32 v82, v82
	v_exp_f32_e32 v83, v83
	v_exp_f32_e32 v84, v84
	v_exp_f32_e32 v85, v85
	v_exp_f32_e32 v86, v86
	v_exp_f32_e32 v87, v87
	v_exp_f32_e32 v88, v88
	v_exp_f32_e32 v89, v89
	v_exp_f32_e32 v90, v90
	v_exp_f32_e32 v91, v91
	v_exp_f32_e32 v92, v92
	v_exp_f32_e32 v93, v93
	v_exp_f32_e32 v94, v94
	v_exp_f32_e32 v95, v95
	s_nop 0
	v_pk_add_f32 v[244:245], v[80:81], v[82:83]
	v_pk_add_f32 v[246:247], v[84:85], v[86:87]
	v_pk_add_f32 v[232:233], v[88:89], v[90:91]
	v_pk_add_f32 v[234:235], v[92:93], v[94:95]
	v_pk_add_f32 v[244:245], v[244:245], v[246:247]
	v_pk_add_f32 v[232:233], v[232:233], v[234:235]
	v_pk_add_f32 v[244:245], v[244:245], v[232:233]
	v_add_f32_e32 v240, v244, v245
	v_cvt_pk_bf16_f32 v8, v80, v81
	v_cvt_pk_bf16_f32 v9, v82, v83
	v_cvt_pk_bf16_f32 v10, v84, v85
	v_cvt_pk_bf16_f32 v11, v86, v87
	v_cvt_pk_bf16_f32 v88, v88, v89
	v_cvt_pk_bf16_f32 v89, v90, v91
	v_cvt_pk_bf16_f32 v90, v92, v93
	v_cvt_pk_bf16_f32 v91, v94, v95
	v_cndmask_b32_e64 v8, 0, v8, s[72:73]
	v_cndmask_b32_e64 v9, 0, v9, s[72:73]
	v_cndmask_b32_e64 v10, 0, v10, s[72:73]
	v_cndmask_b32_e64 v11, 0, v11, s[72:73]
	v_cndmask_b32_e64 v88, 0, v88, s[72:73]
	v_cndmask_b32_e64 v89, 0, v89, s[72:73]
	v_cndmask_b32_e64 v90, 0, v90, s[72:73]
	v_cndmask_b32_e64 v91, 0, v91, s[72:73]
	ds_read_b64_tr_b16 v[80:81], v231 offset:32768
	ds_read_b64_tr_b16 v[82:83], v241 offset:34816
	ds_read_b64_tr_b16 v[84:85], v231 offset:36864
	ds_read_b64_tr_b16 v[86:87], v241 offset:38912
	ds_read_b64_tr_b16 v[92:93], v242 offset:32768
	ds_read_b64_tr_b16 v[94:95], v243 offset:34816
	ds_read_b64_tr_b16 v[236:237], v242 offset:36864
	ds_read_b64_tr_b16 v[238:239], v243 offset:38912
	s_waitcnt lgkmcnt(8)
	v_mfma_f32_32x32x16_bf16 v[64:79], v[8:11], v[12:15], v[64:79]
	v_exp_f32_e32 v96, v96
	v_exp_f32_e32 v97, v97
	v_mfma_f32_32x32x16_bf16 v[64:79], v[88:91], v[208:211], v[64:79]
	v_exp_f32_e32 v98, v98
	v_exp_f32_e32 v99, v99
	ds_read_b64_tr_b16 v[12:13], v0 offset:40960
	ds_read_b64_tr_b16 v[14:15], v6 offset:43008
	ds_read_b64_tr_b16 v[208:209], v0 offset:45056
	ds_read_b64_tr_b16 v[210:211], v6 offset:47104
	v_mfma_f32_32x32x16_bf16 v[48:63], v[8:11], v[212:215], v[48:63]
	v_exp_f32_e32 v100, v100
	v_exp_f32_e32 v101, v101
	v_mfma_f32_32x32x16_bf16 v[48:63], v[88:91], v[216:219], v[48:63]
	v_exp_f32_e32 v102, v102
	v_exp_f32_e32 v103, v103
	ds_read_b64_tr_b16 v[212:213], v7 offset:40960
	ds_read_b64_tr_b16 v[214:215], v230 offset:43008
	ds_read_b64_tr_b16 v[216:217], v7 offset:45056
	ds_read_b64_tr_b16 v[218:219], v230 offset:47104
	s_waitcnt lgkmcnt(8)
	v_mfma_f32_32x32x16_bf16 v[32:47], v[8:11], v[80:83], v[32:47]
	v_exp_f32_e32 v104, v104
	v_exp_f32_e32 v105, v105
	v_mfma_f32_32x32x16_bf16 v[32:47], v[88:91], v[84:87], v[32:47]
	v_exp_f32_e32 v106, v106
	v_exp_f32_e32 v107, v107
	ds_read_b64_tr_b16 v[80:81], v231 offset:40960
	ds_read_b64_tr_b16 v[82:83], v241 offset:43008
	ds_read_b64_tr_b16 v[84:85], v231 offset:45056
	ds_read_b64_tr_b16 v[86:87], v241 offset:47104
	v_mfma_f32_32x32x16_bf16 v[16:31], v[8:11], v[92:95], v[16:31]
	v_exp_f32_e32 v108, v108
	v_exp_f32_e32 v109, v109
	v_mfma_f32_32x32x16_bf16 v[16:31], v[88:91], v[236:239], v[16:31]
	v_exp_f32_e32 v110, v110
	v_exp_f32_e32 v111, v111
	ds_read_b64_tr_b16 v[92:93], v242 offset:40960
	ds_read_b64_tr_b16 v[94:95], v243 offset:43008
	ds_read_b64_tr_b16 v[236:237], v242 offset:45056
	ds_read_b64_tr_b16 v[238:239], v243 offset:47104
	v_pk_add_f32 v[244:245], v[96:97], v[98:99]
	v_pk_add_f32 v[246:247], v[100:101], v[102:103]
	v_pk_add_f32 v[6:7], v[104:105], v[106:107]
	v_pk_add_f32 v[230:231], v[108:109], v[110:111]
	v_pk_add_f32 v[244:245], v[244:245], v[246:247]
	v_pk_add_f32 v[6:7], v[6:7], v[230:231]
	v_pk_add_f32 v[244:245], v[244:245], v[6:7]
	v_add_f32_e32 v244, v244, v245
	v_cvt_pk_bf16_f32 v2, v96, v97
	v_cvt_pk_bf16_f32 v3, v98, v99
	v_cvt_pk_bf16_f32 v4, v100, v101
	v_cvt_pk_bf16_f32 v5, v102, v103
	v_cvt_pk_bf16_f32 v232, v104, v105
	v_cvt_pk_bf16_f32 v233, v106, v107
	v_cvt_pk_bf16_f32 v234, v108, v109
	v_cvt_pk_bf16_f32 v235, v110, v111
	v_cndmask_b32_e64 v2, 0, v2, s[72:73]
	v_cndmask_b32_e64 v3, 0, v3, s[72:73]
	v_cndmask_b32_e64 v4, 0, v4, s[72:73]
	v_cndmask_b32_e64 v5, 0, v5, s[72:73]
	v_cndmask_b32_e64 v232, 0, v232, s[72:73]
	v_cndmask_b32_e64 v233, 0, v233, s[72:73]
	v_cndmask_b32_e64 v234, 0, v234, s[72:73]
	v_cndmask_b32_e64 v235, 0, v235, s[72:73]
	v_add_f32_e32 v240, v240, v244
	v_cndmask_b32_e64 v240, 0, v240, s[72:73]
	v_add_f32_e32 v198, v198, v240
	s_waitcnt lgkmcnt(12)
	v_mfma_f32_32x32x16_bf16 v[64:79], v[2:5], v[12:15], v[64:79]
	v_mfma_f32_32x32x16_bf16 v[64:79], v[232:235], v[208:211], v[64:79]
	s_waitcnt lgkmcnt(8)
	v_mfma_f32_32x32x16_bf16 v[48:63], v[2:5], v[212:215], v[48:63]
	v_mfma_f32_32x32x16_bf16 v[48:63], v[232:235], v[216:219], v[48:63]
	s_waitcnt lgkmcnt(4)
	v_mfma_f32_32x32x16_bf16 v[32:47], v[2:5], v[80:83], v[32:47]
	v_mfma_f32_32x32x16_bf16 v[32:47], v[232:235], v[84:87], v[32:47]
	s_waitcnt lgkmcnt(0)
	v_mfma_f32_32x32x16_bf16 v[16:31], v[2:5], v[92:95], v[16:31]
	v_mfma_f32_32x32x16_bf16 v[16:31], v[232:235], v[236:239], v[16:31]
	s_branch .LBB0_743
